# stack F + EpiStore (P10) rowscale loads hoisted to epilogue start
# speedup vs baseline: 1.0096x; 1.0039x over previous
.LBB0_809:
	v_lshl_add_u32 v150, s6, 8, v159
	v_ashrrev_i32_e32 v151, 31, v150
	v_lshlrev_b64 v[152:153], 6, v[150:151]
	v_lshl_add_u64 v[152:153], v[140:141], 0, v[152:153]
	v_mov_b32_e32 v218, v152
	v_mov_b32_e32 v219, v153
	global_load_dwordx4 v[152:155], v[152:153], off
	global_load_dwordx4 v[188:191], v[218:219], off offset:1024
	global_load_dwordx4 v[192:195], v[218:219], off offset:2048
	global_load_dwordx4 v[196:199], v[218:219], off offset:3072
	v_mov_b32_e32 v216, 0x2000
	v_mov_b32_e32 v217, 0
	v_lshl_add_u64 v[216:217], v[218:219], 0, v[216:217]
	global_load_dwordx4 v[200:203], v[216:217], off
	global_load_dwordx4 v[204:207], v[216:217], off offset:1024
	global_load_dwordx4 v[208:211], v[216:217], off offset:2048
	global_load_dwordx4 v[212:215], v[216:217], off offset:3072
	v_and_b32_e32 v157, 64, v165
	v_xor_b32_e32 v156, 16, v165
	v_add_u32_e32 v168, 64, v157
	v_cmp_lt_i32_e32 vcc, v156, v168
	s_waitcnt vmcnt(0)
	v_mov_b32_e32 v157, v154
	v_cndmask_b32_e32 v156, v165, v156, vcc
	v_lshlrev_b32_e32 v167, 2, v156
	v_mov_b32_e32 v156, v153
	v_mov_b32_e32 v153, v155
	v_pk_add_f32 v[152:153], v[156:157], v[152:153]
	v_xor_b32_e32 v154, 32, v165
	v_add_f32_e32 v152, v152, v153
	v_mov_b32_e32 v153, v152
	s_nop 1
	v_permlane16_swap_b32_e32 v152, v153
	v_cmp_lt_i32_e32 vcc, v154, v168
	s_nop 1
	v_cndmask_b32_e32 v154, v165, v154, vcc
	v_lshlrev_b32_e32 v168, 2, v154
	s_waitcnt lgkmcnt(0)
	v_add_f32_e32 v154, v152, v153
	v_mov_b32_e32 v155, v154
	s_nop 1
	v_permlane32_swap_b32_e32 v154, v155
	v_lshl_or_b32 v152, s0, 8, v161
	v_ashrrev_i32_e32 v153, 31, v152
	s_waitcnt lgkmcnt(0)
	v_add_f32_e32 v154, v154, v155
	v_fmamk_f32 v154, v154, 0x3a800000, v166
	v_mul_f32_e32 v155, 0x4b800000, v154
	v_cmp_gt_f32_e32 vcc, s52, v154
	s_nop 1
	v_cndmask_b32_e32 v154, v154, v155, vcc
	v_rsq_f32_e32 v156, v154
	v_lshlrev_b64 v[154:155], 12, v[150:151]
	v_lshl_add_u64 v[154:155], s[12:13], 0, v[154:155]
	v_lshl_add_u64 v[154:155], v[152:153], 1, v[154:155]
	v_mul_f32_e32 v151, 0x45800000, v156
	v_cndmask_b32_e32 v156, v156, v151, vcc
	v_mov_b32_e32 v157, v156
	v_cmp_gt_i32_e32 vcc, s53, v152
	s_and_saveexec_b64 s[0:1], vcc
	s_cbranch_execz .LBB0_811
	v_mov_b32_e32 v170, v156
	v_mov_b32_e32 v171, v156
	v_pk_mul_f32 v[126:127], v[126:127], v[170:171]
	v_pk_mul_f32 v[124:125], v[124:125], v[156:157]
	v_pk_mul_f32 v[122:123], v[122:123], v[170:171]
	v_pk_mul_f32 v[120:121], v[120:121], v[156:157]
	v_cvt_pk_bf16_f32 v124, v124, v125
	v_cvt_pk_bf16_f32 v125, v126, v127
	v_cvt_pk_bf16_f32 v126, v120, v121
	v_cvt_pk_bf16_f32 v127, v122, v123
	global_store_dwordx4 v[154:155], v[124:127], off

.LBB0_813:
	s_or_b64 exec, exec, s[0:1]
	s_nop 0
	v_or_b32_e32 v116, 16, v150
	v_ashrrev_i32_e32 v117, 31, v116
	v_lshlrev_b64 v[112:113], 6, v[116:117]
	v_lshl_add_u64 v[112:113], v[140:141], 0, v[112:113]
	s_nop 1
	v_mov_b32_e32 v112, v188
	v_mov_b32_e32 v113, v189
	v_mov_b32_e32 v114, v190
	v_mov_b32_e32 v115, v191
	v_mov_b32_e32 v118, v113
	v_mov_b32_e32 v119, v114
	v_mov_b32_e32 v113, v115
	v_pk_add_f32 v[112:113], v[118:119], v[112:113]
	s_nop 0
	v_add_f32_e32 v112, v112, v113
	v_mov_b32_e32 v113, v112
	s_nop 1
	v_permlane16_swap_b32_e32 v112, v113
	s_waitcnt lgkmcnt(0)
	v_add_f32_e32 v112, v112, v113
	v_mov_b32_e32 v113, v112
	s_nop 1
	v_permlane32_swap_b32_e32 v112, v113
	s_waitcnt lgkmcnt(0)
	v_add_f32_e32 v112, v112, v113
	v_fmamk_f32 v112, v112, 0x3a800000, v166
	v_mul_f32_e32 v113, 0x4b800000, v112
	v_cmp_gt_f32_e64 s[0:1], s52, v112
	s_nop 1
	v_cndmask_b32_e64 v112, v112, v113, s[0:1]
	v_rsq_f32_e32 v114, v112
	v_lshlrev_b64 v[112:113], 12, v[116:117]
	v_lshl_add_u64 v[112:113], s[12:13], 0, v[112:113]
	v_lshl_add_u64 v[112:113], v[152:153], 1, v[112:113]
	v_mul_f32_e32 v115, 0x45800000, v114
	v_cndmask_b32_e64 v114, v114, v115, s[0:1]
	v_mov_b32_e32 v115, v114
	s_and_saveexec_b64 s[0:1], vcc
	s_cbranch_execz .LBB0_815
	v_mov_b32_e32 v116, v114
	v_mov_b32_e32 v117, v114
	v_pk_mul_f32 v[110:111], v[110:111], v[116:117]
	v_pk_mul_f32 v[108:109], v[108:109], v[114:115]
	v_pk_mul_f32 v[106:107], v[106:107], v[116:117]
	v_pk_mul_f32 v[104:105], v[104:105], v[114:115]
	v_cvt_pk_bf16_f32 v108, v108, v109
	v_cvt_pk_bf16_f32 v109, v110, v111
	v_cvt_pk_bf16_f32 v110, v104, v105
	v_cvt_pk_bf16_f32 v111, v106, v107
	global_store_dwordx4 v[112:113], v[108:111], off

.LBB0_817:
	s_or_b64 exec, exec, s[0:1]
	s_nop 0
	v_or_b32_e32 v100, 32, v150
	v_ashrrev_i32_e32 v101, 31, v100
	v_lshlrev_b64 v[96:97], 6, v[100:101]
	v_lshl_add_u64 v[96:97], v[140:141], 0, v[96:97]
	s_nop 1
	v_mov_b32_e32 v96, v192
	v_mov_b32_e32 v97, v193
	v_mov_b32_e32 v98, v194
	v_mov_b32_e32 v99, v195
	v_mov_b32_e32 v102, v97
	v_mov_b32_e32 v103, v98
	v_mov_b32_e32 v97, v99
	v_pk_add_f32 v[96:97], v[102:103], v[96:97]
	s_nop 0
	v_add_f32_e32 v96, v96, v97
	v_mov_b32_e32 v97, v96
	s_nop 1
	v_permlane16_swap_b32_e32 v96, v97
	s_waitcnt lgkmcnt(0)
	v_add_f32_e32 v96, v96, v97
	v_mov_b32_e32 v97, v96
	s_nop 1
	v_permlane32_swap_b32_e32 v96, v97
	s_waitcnt lgkmcnt(0)
	v_add_f32_e32 v96, v96, v97
	v_fmamk_f32 v96, v96, 0x3a800000, v166
	v_mul_f32_e32 v97, 0x4b800000, v96
	v_cmp_gt_f32_e64 s[0:1], s52, v96
	s_nop 1
	v_cndmask_b32_e64 v96, v96, v97, s[0:1]
	v_rsq_f32_e32 v98, v96
	v_lshlrev_b64 v[96:97], 12, v[100:101]
	v_lshl_add_u64 v[96:97], s[12:13], 0, v[96:97]
	v_lshl_add_u64 v[96:97], v[152:153], 1, v[96:97]
	v_mul_f32_e32 v99, 0x45800000, v98
	v_cndmask_b32_e64 v98, v98, v99, s[0:1]
	v_mov_b32_e32 v99, v98
	s_and_saveexec_b64 s[0:1], vcc
	s_cbranch_execz .LBB0_819
	v_mov_b32_e32 v100, v98
	v_mov_b32_e32 v101, v98
	v_pk_mul_f32 v[94:95], v[94:95], v[100:101]
	v_pk_mul_f32 v[92:93], v[92:93], v[98:99]
	v_pk_mul_f32 v[90:91], v[90:91], v[100:101]
	v_pk_mul_f32 v[88:89], v[88:89], v[98:99]
	v_cvt_pk_bf16_f32 v92, v92, v93
	v_cvt_pk_bf16_f32 v93, v94, v95
	v_cvt_pk_bf16_f32 v94, v88, v89
	v_cvt_pk_bf16_f32 v95, v90, v91
	global_store_dwordx4 v[96:97], v[92:95], off

.LBB0_821:
	s_or_b64 exec, exec, s[0:1]
	s_nop 0
	v_or_b32_e32 v84, 48, v150
	v_ashrrev_i32_e32 v85, 31, v84
	v_lshlrev_b64 v[80:81], 6, v[84:85]
	v_lshl_add_u64 v[80:81], v[140:141], 0, v[80:81]
	s_nop 1
	v_mov_b32_e32 v80, v196
	v_mov_b32_e32 v81, v197
	v_mov_b32_e32 v82, v198
	v_mov_b32_e32 v83, v199
	v_mov_b32_e32 v86, v81
	v_mov_b32_e32 v87, v82
	v_mov_b32_e32 v81, v83
	v_pk_add_f32 v[80:81], v[86:87], v[80:81]
	s_nop 0
	v_add_f32_e32 v80, v80, v81
	v_mov_b32_e32 v81, v80
	s_nop 1
	v_permlane16_swap_b32_e32 v80, v81
	s_waitcnt lgkmcnt(0)
	v_add_f32_e32 v80, v80, v81
	v_mov_b32_e32 v81, v80
	s_nop 1
	v_permlane32_swap_b32_e32 v80, v81
	s_waitcnt lgkmcnt(0)
	v_add_f32_e32 v80, v80, v81
	v_fmamk_f32 v80, v80, 0x3a800000, v166
	v_mul_f32_e32 v81, 0x4b800000, v80
	v_cmp_gt_f32_e64 s[0:1], s52, v80
	s_nop 1
	v_cndmask_b32_e64 v80, v80, v81, s[0:1]
	v_rsq_f32_e32 v82, v80
	v_lshlrev_b64 v[80:81], 12, v[84:85]
	v_lshl_add_u64 v[80:81], s[12:13], 0, v[80:81]
	v_lshl_add_u64 v[80:81], v[152:153], 1, v[80:81]
	v_mul_f32_e32 v83, 0x45800000, v82
	v_cndmask_b32_e64 v82, v82, v83, s[0:1]
	v_mov_b32_e32 v83, v82
	s_and_saveexec_b64 s[0:1], vcc
	s_cbranch_execz .LBB0_823
	v_mov_b32_e32 v84, v82
	v_mov_b32_e32 v85, v82
	v_pk_mul_f32 v[78:79], v[78:79], v[84:85]
	v_pk_mul_f32 v[76:77], v[76:77], v[82:83]
	v_pk_mul_f32 v[74:75], v[74:75], v[84:85]
	v_pk_mul_f32 v[72:73], v[72:73], v[82:83]
	v_cvt_pk_bf16_f32 v76, v76, v77
	v_cvt_pk_bf16_f32 v77, v78, v79
	v_cvt_pk_bf16_f32 v78, v72, v73
	v_cvt_pk_bf16_f32 v79, v74, v75
	global_store_dwordx4 v[80:81], v[76:79], off

.LBB0_825:
	s_or_b64 exec, exec, s[0:1]
	s_nop 0
	v_add_u32_e32 v68, 0x80, v150
	v_ashrrev_i32_e32 v69, 31, v68
	v_lshlrev_b64 v[64:65], 6, v[68:69]
	v_lshl_add_u64 v[64:65], v[140:141], 0, v[64:65]
	s_nop 1
	v_mov_b32_e32 v64, v200
	v_mov_b32_e32 v65, v201
	v_mov_b32_e32 v66, v202
	v_mov_b32_e32 v67, v203
	v_mov_b32_e32 v70, v65
	v_mov_b32_e32 v71, v66
	v_mov_b32_e32 v65, v67
	v_pk_add_f32 v[64:65], v[70:71], v[64:65]
	s_nop 0
	v_add_f32_e32 v64, v64, v65
	v_mov_b32_e32 v65, v64
	s_nop 1
	v_permlane16_swap_b32_e32 v64, v65
	s_waitcnt lgkmcnt(0)
	v_add_f32_e32 v64, v64, v65
	v_mov_b32_e32 v65, v64
	s_nop 1
	v_permlane32_swap_b32_e32 v64, v65
	s_waitcnt lgkmcnt(0)
	v_add_f32_e32 v64, v64, v65
	v_fmamk_f32 v64, v64, 0x3a800000, v166
	v_mul_f32_e32 v65, 0x4b800000, v64
	v_cmp_gt_f32_e64 s[0:1], s52, v64
	s_nop 1
	v_cndmask_b32_e64 v64, v64, v65, s[0:1]
	v_rsq_f32_e32 v66, v64
	v_lshlrev_b64 v[64:65], 12, v[68:69]
	v_lshl_add_u64 v[64:65], s[12:13], 0, v[64:65]
	v_lshl_add_u64 v[64:65], v[152:153], 1, v[64:65]
	v_mul_f32_e32 v67, 0x45800000, v66
	v_cndmask_b32_e64 v66, v66, v67, s[0:1]
	v_mov_b32_e32 v67, v66
	s_and_saveexec_b64 s[0:1], vcc
	s_cbranch_execz .LBB0_827
	v_mov_b32_e32 v68, v66
	v_mov_b32_e32 v69, v66
	v_pk_mul_f32 v[62:63], v[62:63], v[68:69]
	v_pk_mul_f32 v[60:61], v[60:61], v[66:67]
	v_pk_mul_f32 v[58:59], v[58:59], v[68:69]
	v_pk_mul_f32 v[56:57], v[56:57], v[66:67]
	v_cvt_pk_bf16_f32 v60, v60, v61
	v_cvt_pk_bf16_f32 v61, v62, v63
	v_cvt_pk_bf16_f32 v62, v56, v57
	v_cvt_pk_bf16_f32 v63, v58, v59
	global_store_dwordx4 v[64:65], v[60:63], off

.LBB0_829:
	s_or_b64 exec, exec, s[0:1]
	s_nop 0
	v_add_u32_e32 v52, 0x90, v150
	v_ashrrev_i32_e32 v53, 31, v52
	v_lshlrev_b64 v[48:49], 6, v[52:53]
	v_lshl_add_u64 v[48:49], v[140:141], 0, v[48:49]
	s_nop 1
	v_mov_b32_e32 v48, v204
	v_mov_b32_e32 v49, v205
	v_mov_b32_e32 v50, v206
	v_mov_b32_e32 v51, v207
	v_mov_b32_e32 v54, v49
	v_mov_b32_e32 v55, v50
	v_mov_b32_e32 v49, v51
	v_pk_add_f32 v[48:49], v[54:55], v[48:49]
	s_nop 0
	v_add_f32_e32 v48, v48, v49
	v_mov_b32_e32 v49, v48
	s_nop 1
	v_permlane16_swap_b32_e32 v48, v49
	s_waitcnt lgkmcnt(0)
	v_add_f32_e32 v48, v48, v49
	v_mov_b32_e32 v49, v48
	s_nop 1
	v_permlane32_swap_b32_e32 v48, v49
	s_waitcnt lgkmcnt(0)
	v_add_f32_e32 v48, v48, v49
	v_fmamk_f32 v48, v48, 0x3a800000, v166
	v_mul_f32_e32 v49, 0x4b800000, v48
	v_cmp_gt_f32_e64 s[0:1], s52, v48
	s_nop 1
	v_cndmask_b32_e64 v48, v48, v49, s[0:1]
	v_rsq_f32_e32 v50, v48
	v_lshlrev_b64 v[48:49], 12, v[52:53]
	v_lshl_add_u64 v[48:49], s[12:13], 0, v[48:49]
	v_lshl_add_u64 v[48:49], v[152:153], 1, v[48:49]
	v_mul_f32_e32 v51, 0x45800000, v50
	v_cndmask_b32_e64 v50, v50, v51, s[0:1]
	v_mov_b32_e32 v51, v50
	s_and_saveexec_b64 s[0:1], vcc
	s_cbranch_execz .LBB0_831
	v_mov_b32_e32 v52, v50
	v_mov_b32_e32 v53, v50
	v_pk_mul_f32 v[46:47], v[46:47], v[52:53]
	v_pk_mul_f32 v[44:45], v[44:45], v[50:51]
	v_pk_mul_f32 v[42:43], v[42:43], v[52:53]
	v_pk_mul_f32 v[40:41], v[40:41], v[50:51]
	v_cvt_pk_bf16_f32 v44, v44, v45
	v_cvt_pk_bf16_f32 v45, v46, v47
	v_cvt_pk_bf16_f32 v46, v40, v41
	v_cvt_pk_bf16_f32 v47, v42, v43
	global_store_dwordx4 v[48:49], v[44:47], off

.LBB0_833:
	s_or_b64 exec, exec, s[0:1]
	s_nop 0
	v_add_u32_e32 v36, 0xa0, v150
	v_ashrrev_i32_e32 v37, 31, v36
	v_lshlrev_b64 v[32:33], 6, v[36:37]
	v_lshl_add_u64 v[32:33], v[140:141], 0, v[32:33]
	s_nop 1
	v_mov_b32_e32 v32, v208
	v_mov_b32_e32 v33, v209
	v_mov_b32_e32 v34, v210
	v_mov_b32_e32 v35, v211
	v_mov_b32_e32 v38, v33
	v_mov_b32_e32 v39, v34
	v_mov_b32_e32 v33, v35
	v_pk_add_f32 v[32:33], v[38:39], v[32:33]
	s_nop 0
	v_add_f32_e32 v32, v32, v33
	v_mov_b32_e32 v33, v32
	s_nop 1
	v_permlane16_swap_b32_e32 v32, v33
	s_waitcnt lgkmcnt(0)
	v_add_f32_e32 v32, v32, v33
	v_mov_b32_e32 v33, v32
	s_nop 1
	v_permlane32_swap_b32_e32 v32, v33
	s_waitcnt lgkmcnt(0)
	v_add_f32_e32 v32, v32, v33
	v_fmamk_f32 v32, v32, 0x3a800000, v166
	v_mul_f32_e32 v33, 0x4b800000, v32
	v_cmp_gt_f32_e64 s[0:1], s52, v32
	s_nop 1
	v_cndmask_b32_e64 v32, v32, v33, s[0:1]
	v_rsq_f32_e32 v34, v32
	v_lshlrev_b64 v[32:33], 12, v[36:37]
	v_lshl_add_u64 v[32:33], s[12:13], 0, v[32:33]
	v_lshl_add_u64 v[32:33], v[152:153], 1, v[32:33]
	v_mul_f32_e32 v35, 0x45800000, v34
	v_cndmask_b32_e64 v34, v34, v35, s[0:1]
	v_mov_b32_e32 v35, v34
	s_and_saveexec_b64 s[0:1], vcc
	s_cbranch_execz .LBB0_835
	v_mov_b32_e32 v36, v34
	v_mov_b32_e32 v37, v34
	v_pk_mul_f32 v[30:31], v[30:31], v[36:37]
	v_pk_mul_f32 v[28:29], v[28:29], v[34:35]
	v_pk_mul_f32 v[26:27], v[26:27], v[36:37]
	v_pk_mul_f32 v[24:25], v[24:25], v[34:35]
	v_cvt_pk_bf16_f32 v28, v28, v29
	v_cvt_pk_bf16_f32 v29, v30, v31
	v_cvt_pk_bf16_f32 v30, v24, v25
	v_cvt_pk_bf16_f32 v31, v26, v27
	global_store_dwordx4 v[32:33], v[28:31], off

.LBB0_837:
	s_or_b64 exec, exec, s[0:1]
	s_nop 0
	v_add_u32_e32 v20, 0xb0, v150
	v_ashrrev_i32_e32 v21, 31, v20
	v_lshlrev_b64 v[16:17], 6, v[20:21]
	v_lshl_add_u64 v[16:17], v[140:141], 0, v[16:17]
	s_nop 1
	v_mov_b32_e32 v16, v212
	v_mov_b32_e32 v17, v213
	v_mov_b32_e32 v18, v214
	v_mov_b32_e32 v19, v215
	v_mov_b32_e32 v22, v17
	v_mov_b32_e32 v23, v18
	v_mov_b32_e32 v17, v19
	v_pk_add_f32 v[16:17], v[22:23], v[16:17]
	s_nop 0
	v_add_f32_e32 v16, v16, v17
	v_mov_b32_e32 v17, v16
	s_nop 1
	v_permlane16_swap_b32_e32 v16, v17
	s_waitcnt lgkmcnt(0)
	v_add_f32_e32 v16, v16, v17
	v_mov_b32_e32 v17, v16
	s_nop 1
	v_permlane32_swap_b32_e32 v16, v17
	s_waitcnt lgkmcnt(0)
	v_add_f32_e32 v16, v16, v17
	v_fmamk_f32 v16, v16, 0x3a800000, v166
	v_mul_f32_e32 v17, 0x4b800000, v16
	v_cmp_gt_f32_e64 s[0:1], s52, v16
	s_nop 1
	v_cndmask_b32_e64 v16, v16, v17, s[0:1]
	v_rsq_f32_e32 v18, v16
	v_lshlrev_b64 v[16:17], 12, v[20:21]
	v_lshl_add_u64 v[16:17], s[12:13], 0, v[16:17]
	v_lshl_add_u64 v[16:17], v[152:153], 1, v[16:17]
	v_mul_f32_e32 v19, 0x45800000, v18
	v_cndmask_b32_e64 v18, v18, v19, s[0:1]
	v_mov_b32_e32 v19, v18
	s_and_saveexec_b64 s[0:1], vcc
	s_cbranch_execnz .LBB0_840
	s_or_b64 exec, exec, s[0:1]
	s_and_saveexec_b64 s[0:1], s[6:7]
	s_cbranch_execnz .LBB0_841
